# prep_dt: serial per-thread 128-step scans replaced by a workgroup-parallel pass (4-step segments, 32-lane DPP scan, vector stores)
# baseline (speedup 1.0000x reference)
.LBB0_657:
	s_or_b64 exec, exec, s[38:39]
	v_lshl_or_b32 v0, v6, 6, v0
	v_cmp_gt_i32_e32 vcc, 16, v3
	ds_write_b32 v0, v1
	s_waitcnt lgkmcnt(0)
	s_barrier
	s_mov_b64 s[38:39], exec
	v_lshrrev_b32_e32 v4, 5, v206
	v_and_b32_e32 v5, 31, v206
	v_lshrrev_b32_e32 v6, 6, v206
	v_readlane_b32 s48, v237, 23
	v_readfirstlane_b32 s98, v6
	v_readlane_b32 s49, v237, 24
	s_lshr_b32 s99, s98, 2
	s_lshl_b32 s100, s36, 4
	v_add_u32_e32 v7, s100, v4
	v_lshlrev_b32_e32 v7, 2, v7
	v_lshlrev_b32_e32 v9, 2, v5
	s_cmp_eq_u32 s99, 0
	s_cbranch_scc1 .Lpdt_f0
	v_sub_u32_e32 v9, 0x7c, v9
.Lpdt_f0:
	global_load_dword v8, v7, s[48:49]
	v_lshlrev_b32_e32 v10, 6, v9
	v_lshl_add_u32 v10, v4, 2, v10
	ds_read_b32 v12, v10
	ds_read_b32 v13, v10 offset:64
	ds_read_b32 v14, v10 offset:128
	ds_read_b32 v15, v10 offset:192
	s_waitcnt vmcnt(0) lgkmcnt(0)
	s_cmp_eq_u32 s99, 0
	s_cbranch_scc1 .Lpdt_f1
	v_mov_b32_e32 v34, v12
	v_mov_b32_e32 v12, v15
	v_mov_b32_e32 v15, v34
	v_mov_b32_e32 v34, v13
	v_mov_b32_e32 v13, v14
	v_mov_b32_e32 v14, v34
.Lpdt_f1:
	v_mul_f32_e32 v34, 0x3fb8aa3b, v8
	v_fma_f32 v17, v8, s84, -v34
	v_rndne_f32_e32 v18, v34
	v_fmac_f32_e32 v17, 0x32a5705f, v8
	v_sub_f32_e32 v34, v34, v18
	v_add_f32_e32 v34, v34, v17
	v_exp_f32_e32 v34, v34
	v_cvt_i32_f32_e32 v17, v18
	v_cmp_ngt_f32_e32 vcc, s87, v8
	s_nop 0
	v_ldexp_f32 v34, v34, v17
	v_cndmask_b32_e32 v34, 0, v34, vcc
	v_cmp_nlt_f32_e32 vcc, s88, v8
	s_nop 1
	v_cndmask_b32_e32 v34, v216, v34, vcc
	v_mul_f32_e64 v20, v12, -v34
	v_fma_f32 v21, v13, -v34, v20
	v_fma_f32 v22, v14, -v34, v21
	v_fma_f32 v23, v15, -v34, v22
	v_mov_b32_e32 v24, v23
	s_nop 1
	v_add_f32_dpp v24, v24, v24 row_shr:1 row_mask:0xf bank_mask:0xf bound_ctrl:0
	s_nop 1
	v_add_f32_dpp v24, v24, v24 row_shr:2 row_mask:0xf bank_mask:0xf bound_ctrl:0
	s_nop 1
	v_add_f32_dpp v24, v24, v24 row_shr:4 row_mask:0xf bank_mask:0xf bound_ctrl:0
	s_nop 1
	v_add_f32_dpp v24, v24, v24 row_shr:8 row_mask:0xf bank_mask:0xf bound_ctrl:0
	s_nop 1
	v_add_f32_dpp v24, v24, v24 row_bcast:15 row_mask:0xa bank_mask:0xf
	s_nop 1
	v_readlane_b32 s50, v24, 31
	v_readlane_b32 s51, v24, 63
	v_sub_f32_e32 v25, v24, v23
	v_mov_b32_e32 v26, s50
	s_mov_b64 s[100:101], exec
	s_mov_b32 exec_lo, 0
	v_mov_b32_e32 v26, s51
	s_mov_b64 exec, s[100:101]
	v_add_f32_e32 v20, v25, v20
	v_add_f32_e32 v21, v25, v21
	v_add_f32_e32 v22, v25, v22
	v_add_f32_e32 v23, v25, v23
	v_sub_f32_e32 v28, v26, v20
	v_sub_f32_e32 v29, v26, v21
	v_sub_f32_e32 v30, v26, v22
	v_sub_f32_e32 v31, v26, v23
	v_mul_f32_e32 v28, 0x3fb8aa3b, v28
	v_mul_f32_e32 v29, 0x3fb8aa3b, v29
	v_mul_f32_e32 v30, 0x3fb8aa3b, v30
	v_mul_f32_e32 v31, 0x3fb8aa3b, v31
	v_exp_f32_e32 v28, v28
	v_exp_f32_e32 v29, v29
	v_exp_f32_e32 v30, v30
	v_exp_f32_e32 v31, v31
	s_nop 0
	v_mul_f32_e32 v28, v12, v28
	v_mul_f32_e32 v29, v13, v29
	v_mul_f32_e32 v30, v14, v30
	v_mul_f32_e32 v31, v15, v31
	s_cmp_eq_u32 s99, 0
	s_cbranch_scc1 .Lpdt_f2
	v_mov_b32_e32 v32, v12
	v_mov_b32_e32 v12, v15
	v_mov_b32_e32 v15, v32
	v_mov_b32_e32 v32, v13
	v_mov_b32_e32 v13, v14
	v_mov_b32_e32 v14, v32
	v_mov_b32_e32 v32, v20
	v_mov_b32_e32 v20, v23
	v_mov_b32_e32 v23, v32
	v_mov_b32_e32 v32, v21
	v_mov_b32_e32 v21, v22
	v_mov_b32_e32 v22, v32
	v_mov_b32_e32 v32, v28
	v_mov_b32_e32 v28, v31
	v_mov_b32_e32 v31, v32
	v_mov_b32_e32 v32, v29
	v_mov_b32_e32 v29, v30
	v_mov_b32_e32 v30, v32
.Lpdt_f2:
	s_sub_u32 s35, s60, 0x630
	s_lshl_b32 s35, s35, 4
	v_add_u32_e32 v33, s35, v4
	v_lshlrev_b32_e32 v33, 9, v33
	v_lshl_add_u32 v33, v9, 2, v33
	s_add_u32 s48, s96, 0xca84000
	s_addc_u32 s49, s97, 0
	global_store_dwordx4 v33, v[12:15], s[48:49]
	s_add_u32 s48, s96, 0xcae4000
	s_addc_u32 s49, s97, 0
	global_store_dwordx4 v33, v[20:23], s[48:49]
	s_add_u32 s48, s96, 0xcb44000
	s_addc_u32 s49, s97, 0
	global_store_dwordx4 v33, v[28:31], s[48:49]
